# v121: grid barrier followers poll the global generation word instead of the per-XCD one (one republish hop less), on top of v120
# speedup vs baseline: 1.0055x; 1.0004x over previous
.LBB0_70:
	s_or_b64 exec, exec, s[28:29]
	v_cvt_f32_u32_e32 v4, v2
	s_waitcnt vmcnt(0)
	v_readfirstlane_b32 s3, v3
	v_sub_u32_e32 v3, 0, v2
	v_rcp_iflag_f32_e32 v4, v4
	v_add_u32_e32 v5, s3, v1
	v_mul_f32_e32 v4, 0x4f7ffffe, v4
	v_cvt_u32_f32_e32 v4, v4
	v_mul_lo_u32 v1, v3, v4
	v_mul_hi_u32 v1, v4, v1
	v_add_u32_e32 v1, v4, v1
	v_mul_hi_u32 v1, v5, v1
	v_mul_lo_u32 v3, v1, v2
	v_sub_u32_e32 v3, v5, v3
	v_add_u32_e32 v4, 1, v1
	v_cmp_ge_u32_e32 vcc, v3, v2
	s_nop 1
	v_cndmask_b32_e32 v1, v1, v4, vcc
	v_sub_u32_e32 v4, v3, v2
	v_cndmask_b32_e32 v3, v3, v4, vcc
	v_add_u32_e32 v4, 1, v1
	v_cmp_ge_u32_e32 vcc, v3, v2
	v_add_u32_e32 v3, 1, v5
	s_nop 0
	v_cndmask_b32_e32 v1, v1, v4, vcc
	v_mul_lo_u32 v4, v2, v1
	v_add_u32_e32 v2, v4, v2
	v_cmp_ne_u32_e32 vcc, v3, v2
	s_and_saveexec_b64 s[24:25], vcc
	s_xor_b64 s[24:25], exec, s[24:25]
	s_cbranch_execz .LBB0_84
	s_waitcnt lgkmcnt(0)
	v_mov_b32_e32 v0, 0x60d3500
	global_load_dword v0, v0, s[42:43] sc1
	s_add_u32 s34, s42, 0x60d3500
	s_addc_u32 s35, s43, 0
	s_waitcnt vmcnt(0)
	v_cmp_eq_u32_e32 vcc, v0, v1
	s_and_saveexec_b64 s[28:29], vcc
	s_cbranch_execz .LBB0_83
	s_add_u32 s30, s42, 0x60d0200
	s_addc_u32 s31, s43, 0
	s_mov_b32 s3, 1
	s_mov_b64 s[36:37], 0
	v_mov_b32_e32 v0, 0
	s_branch .LBB0_74

.LBB0_101:
	s_or_b64 exec, exec, s[24:25]
	s_mov_b64 s[24:25], exec
	v_mbcnt_lo_u32_b32 v0, s24, 0
	v_mbcnt_hi_u32_b32 v0, s25, v0
	v_cmp_eq_u32_e32 vcc, 0, v0
	s_waitcnt vmcnt(0)
	buffer_inv sc1
	s_and_saveexec_b64 s[28:29], vcc
	s_cbranch_execz .LBB0_103
	s_bcnt1_i32_b64 s3, s[24:25]
.LBB0_103:
	s_or_b64 exec, exec, s[28:29]
	s_waitcnt vmcnt(0)

.LBB0_127:
	s_or_b64 exec, exec, s[8:9]
	v_cvt_f32_u32_e32 v4, v2
	s_waitcnt vmcnt(0)
	v_readfirstlane_b32 s4, v3
	v_sub_u32_e32 v3, 0, v2
	v_rcp_iflag_f32_e32 v4, v4
	v_add_u32_e32 v5, s4, v1
	v_mul_f32_e32 v4, 0x4f7ffffe, v4
	v_cvt_u32_f32_e32 v4, v4
	v_mul_lo_u32 v1, v3, v4
	v_mul_hi_u32 v1, v4, v1
	v_add_u32_e32 v1, v4, v1
	v_mul_hi_u32 v1, v5, v1
	v_mul_lo_u32 v3, v1, v2
	v_sub_u32_e32 v3, v5, v3
	v_add_u32_e32 v4, 1, v1
	v_cmp_ge_u32_e32 vcc, v3, v2
	s_nop 1
	v_cndmask_b32_e32 v1, v1, v4, vcc
	v_sub_u32_e32 v4, v3, v2
	v_cndmask_b32_e32 v3, v3, v4, vcc
	v_add_u32_e32 v4, 1, v1
	v_cmp_ge_u32_e32 vcc, v3, v2
	v_add_u32_e32 v3, 1, v5
	s_nop 0
	v_cndmask_b32_e32 v1, v1, v4, vcc
	v_mul_lo_u32 v4, v2, v1
	v_add_u32_e32 v2, v4, v2
	v_cmp_ne_u32_e32 vcc, v3, v2
	s_and_saveexec_b64 s[4:5], vcc
	s_xor_b64 s[4:5], exec, s[4:5]
	s_cbranch_execz .LBB0_141
	s_waitcnt lgkmcnt(0)
	v_mov_b32_e32 v0, 0x60d3500
	global_load_dword v0, v0, s[42:43] sc1
	s_add_u32 s18, s42, 0x60d3500
	s_addc_u32 s19, s43, 0
	s_waitcnt vmcnt(0)
	v_cmp_eq_u32_e32 vcc, v0, v1
	s_and_saveexec_b64 s[8:9], vcc
	s_cbranch_execz .LBB0_140
	s_add_u32 s16, s42, 0x60d0200
	s_addc_u32 s17, s43, 0
	s_mov_b32 s33, 1
	s_mov_b64 s[24:25], 0
	v_mov_b32_e32 v0, 0
	s_branch .LBB0_131

.LBB0_158:
	s_or_b64 exec, exec, s[4:5]
	s_mov_b64 s[4:5], exec
	v_mbcnt_lo_u32_b32 v0, s4, 0
	v_mbcnt_hi_u32_b32 v0, s5, v0
	v_cmp_eq_u32_e32 vcc, 0, v0
	s_waitcnt vmcnt(0)
	buffer_inv sc1
	s_and_saveexec_b64 s[8:9], vcc
	s_cbranch_execz .LBB0_160
	s_bcnt1_i32_b64 s4, s[4:5]
.LBB0_160:
	s_or_b64 exec, exec, s[8:9]
	s_waitcnt vmcnt(0)

.LBB0_199:
	s_or_b64 exec, exec, s[6:7]
	v_cvt_f32_u32_e32 v4, v2
	s_waitcnt vmcnt(0)
	v_readfirstlane_b32 s4, v3
	v_sub_u32_e32 v3, 0, v2
	v_rcp_iflag_f32_e32 v4, v4
	v_add_u32_e32 v5, s4, v1
	v_mul_f32_e32 v4, 0x4f7ffffe, v4
	v_cvt_u32_f32_e32 v4, v4
	v_mul_lo_u32 v1, v3, v4
	v_mul_hi_u32 v1, v4, v1
	v_add_u32_e32 v1, v4, v1
	v_mul_hi_u32 v1, v5, v1
	v_mul_lo_u32 v3, v1, v2
	v_sub_u32_e32 v3, v5, v3
	v_add_u32_e32 v4, 1, v1
	v_cmp_ge_u32_e32 vcc, v3, v2
	s_nop 1
	v_cndmask_b32_e32 v1, v1, v4, vcc
	v_sub_u32_e32 v4, v3, v2
	v_cndmask_b32_e32 v3, v3, v4, vcc
	v_add_u32_e32 v4, 1, v1
	v_cmp_ge_u32_e32 vcc, v3, v2
	v_add_u32_e32 v3, 1, v5
	s_nop 0
	v_cndmask_b32_e32 v1, v1, v4, vcc
	v_mul_lo_u32 v4, v2, v1
	v_add_u32_e32 v2, v4, v2
	v_cmp_ne_u32_e32 vcc, v3, v2
	s_and_saveexec_b64 s[4:5], vcc
	s_xor_b64 s[4:5], exec, s[4:5]
	s_cbranch_execz .LBB0_213
	s_waitcnt lgkmcnt(0)
	v_mov_b32_e32 v0, 0x60d3500
	global_load_dword v0, v0, s[42:43] sc1
	s_add_u32 s16, s42, 0x60d3500
	s_addc_u32 s17, s43, 0
	s_waitcnt vmcnt(0)
	v_cmp_eq_u32_e32 vcc, v0, v1
	s_and_saveexec_b64 s[6:7], vcc
	s_cbranch_execz .LBB0_212
	s_add_u32 s8, s42, 0x60d0200
	s_addc_u32 s9, s43, 0
	s_mov_b32 s33, 1
	s_mov_b64 s[18:19], 0
	v_mov_b32_e32 v0, 0
	s_branch .LBB0_203

.LBB0_230:
	s_or_b64 exec, exec, s[4:5]
	s_mov_b64 s[4:5], exec
	v_mbcnt_lo_u32_b32 v0, s4, 0
	v_mbcnt_hi_u32_b32 v0, s5, v0
	v_cmp_eq_u32_e32 vcc, 0, v0
	s_waitcnt vmcnt(0)
	buffer_inv sc1
	s_and_saveexec_b64 s[6:7], vcc
	s_cbranch_execz .LBB0_232
	s_bcnt1_i32_b64 s4, s[4:5]
.LBB0_232:
	s_or_b64 exec, exec, s[6:7]
	s_waitcnt vmcnt(0)

.LBB0_262:
	s_or_b64 exec, exec, s[6:7]
	v_cvt_f32_u32_e32 v4, v2
	s_waitcnt vmcnt(0)
	v_readfirstlane_b32 s4, v3
	v_sub_u32_e32 v3, 0, v2
	v_rcp_iflag_f32_e32 v4, v4
	v_add_u32_e32 v5, s4, v1
	v_mul_f32_e32 v4, 0x4f7ffffe, v4
	v_cvt_u32_f32_e32 v4, v4
	v_mul_lo_u32 v1, v3, v4
	v_mul_hi_u32 v1, v4, v1
	v_add_u32_e32 v1, v4, v1
	v_mul_hi_u32 v1, v5, v1
	v_mul_lo_u32 v3, v1, v2
	v_sub_u32_e32 v3, v5, v3
	v_add_u32_e32 v4, 1, v1
	v_cmp_ge_u32_e32 vcc, v3, v2
	s_nop 1
	v_cndmask_b32_e32 v1, v1, v4, vcc
	v_sub_u32_e32 v4, v3, v2
	v_cndmask_b32_e32 v3, v3, v4, vcc
	v_add_u32_e32 v4, 1, v1
	v_cmp_ge_u32_e32 vcc, v3, v2
	v_add_u32_e32 v3, 1, v5
	s_nop 0
	v_cndmask_b32_e32 v1, v1, v4, vcc
	v_mul_lo_u32 v4, v2, v1
	v_add_u32_e32 v2, v4, v2
	v_cmp_ne_u32_e32 vcc, v3, v2
	s_and_saveexec_b64 s[4:5], vcc
	s_xor_b64 s[4:5], exec, s[4:5]
	s_cbranch_execz .LBB0_276
	s_waitcnt lgkmcnt(0)
	v_mov_b32_e32 v0, 0x60d3500
	global_load_dword v0, v0, s[42:43] sc1
	s_add_u32 s16, s42, 0x60d3500
	s_addc_u32 s17, s43, 0
	s_waitcnt vmcnt(0)
	v_cmp_eq_u32_e32 vcc, v0, v1
	s_and_saveexec_b64 s[6:7], vcc
	s_cbranch_execz .LBB0_275
	s_add_u32 s8, s42, 0x60d0200
	s_addc_u32 s9, s43, 0
	s_mov_b32 s11, 1
	s_mov_b64 s[18:19], 0
	v_mov_b32_e32 v0, 0
	s_branch .LBB0_266

.LBB0_293:
	s_or_b64 exec, exec, s[4:5]
	s_mov_b64 s[4:5], exec
	v_mbcnt_lo_u32_b32 v0, s4, 0
	v_mbcnt_hi_u32_b32 v0, s5, v0
	v_cmp_eq_u32_e32 vcc, 0, v0
	s_waitcnt vmcnt(0)
	buffer_inv sc1
	s_and_saveexec_b64 s[6:7], vcc
	s_cbranch_execz .LBB0_295
	s_bcnt1_i32_b64 s4, s[4:5]
.LBB0_295:
	s_or_b64 exec, exec, s[6:7]
	s_waitcnt vmcnt(0)

.LBB0_338:
	s_or_b64 exec, exec, s[8:9]
	v_cvt_f32_u32_e32 v4, v2
	s_waitcnt vmcnt(0)
	v_readfirstlane_b32 s6, v3
	v_sub_u32_e32 v3, 0, v2
	v_rcp_iflag_f32_e32 v4, v4
	v_add_u32_e32 v5, s6, v1
	v_mul_f32_e32 v4, 0x4f7ffffe, v4
	v_cvt_u32_f32_e32 v4, v4
	v_mul_lo_u32 v1, v3, v4
	v_mul_hi_u32 v1, v4, v1
	v_add_u32_e32 v1, v4, v1
	v_mul_hi_u32 v1, v5, v1
	v_mul_lo_u32 v3, v1, v2
	v_sub_u32_e32 v3, v5, v3
	v_add_u32_e32 v4, 1, v1
	v_cmp_ge_u32_e32 vcc, v3, v2
	s_nop 1
	v_cndmask_b32_e32 v1, v1, v4, vcc
	v_sub_u32_e32 v4, v3, v2
	v_cndmask_b32_e32 v3, v3, v4, vcc
	v_add_u32_e32 v4, 1, v1
	v_cmp_ge_u32_e32 vcc, v3, v2
	v_add_u32_e32 v3, 1, v5
	s_nop 0
	v_cndmask_b32_e32 v1, v1, v4, vcc
	v_mul_lo_u32 v4, v2, v1
	v_add_u32_e32 v2, v4, v2
	v_cmp_ne_u32_e32 vcc, v3, v2
	s_and_saveexec_b64 s[6:7], vcc
	s_xor_b64 s[6:7], exec, s[6:7]
	s_cbranch_execz .LBB0_352
	s_waitcnt lgkmcnt(0)
	v_mov_b32_e32 v0, 0x60d3500
	global_load_dword v0, v0, s[42:43] sc1
	s_add_u32 s18, s42, 0x60d3500
	s_addc_u32 s19, s43, 0
	s_waitcnt vmcnt(0)
	v_cmp_eq_u32_e32 vcc, v0, v1
	s_and_saveexec_b64 s[8:9], vcc
	s_cbranch_execz .LBB0_351
	s_add_u32 s16, s42, 0x60d0200
	s_addc_u32 s17, s43, 0
	s_mov_b32 s11, 1
	s_mov_b64 s[20:21], 0
	v_mov_b32_e32 v0, 0
	s_branch .LBB0_342

.LBB0_369:
	s_or_b64 exec, exec, s[6:7]
	s_mov_b64 s[6:7], exec
	v_mbcnt_lo_u32_b32 v0, s6, 0
	v_mbcnt_hi_u32_b32 v0, s7, v0
	v_cmp_eq_u32_e32 vcc, 0, v0
	s_waitcnt vmcnt(0)
	buffer_inv sc1
	s_and_saveexec_b64 s[8:9], vcc
	s_cbranch_execz .LBB0_371
	s_bcnt1_i32_b64 s6, s[6:7]
.LBB0_371:
	s_or_b64 exec, exec, s[8:9]
	s_waitcnt vmcnt(0)

.LBB0_426:
	s_or_b64 exec, exec, s[4:5]
	s_mov_b64 s[4:5], exec
	v_mbcnt_lo_u32_b32 v0, s4, 0
	v_mbcnt_hi_u32_b32 v0, s5, v0
	v_cmp_eq_u32_e32 vcc, 0, v0
	s_waitcnt vmcnt(0)
	buffer_inv sc1
	s_and_saveexec_b64 s[6:7], vcc
	s_cbranch_execz .LBB0_428
	s_bcnt1_i32_b64 s4, s[4:5]
.LBB0_428:
	s_or_b64 exec, exec, s[6:7]
	s_waitcnt vmcnt(0)
